# v46 + attention next-tile K/V ds_write staging hoisted before the last PV MFMA group, blanket vmcnt(0) before the staging writes replaced by the counted vmcnt(2)/(1)/(0) ladder
# baseline (speedup 1.0000x reference)
.LBB0_1217:
	v_lshl_add_u32 v94, s33, 14, v175
	ds_read_b64_tr_b16 v[82:83], v94 offset:0
	ds_read_b64_tr_b16 v[84:85], v94 offset:0x800
	ds_read_b64_tr_b16 v[86:87], v94 offset:0x1000
	ds_read_b64_tr_b16 v[88:89], v94 offset:0x1800
	ds_read_b64_tr_b16 v[90:91], v94 offset:0x2000
	ds_read_b64_tr_b16 v[92:93], v94 offset:0x2800
	ds_read_b64_tr_b16 v[190:191], v94 offset:0x3000
	ds_read_b64_tr_b16 v[192:193], v94 offset:0x3800
	ds_read_b64_tr_b16 v[194:195], v94 offset:0x200
	ds_read_b64_tr_b16 v[196:197], v94 offset:0xa00
	ds_read_b64_tr_b16 v[198:199], v94 offset:0x1200
	ds_read_b64_tr_b16 v[200:201], v94 offset:0x1a00
	ds_read_b64_tr_b16 v[202:203], v94 offset:0x2200
	ds_read_b64_tr_b16 v[204:205], v94 offset:0x2a00
	ds_read_b64_tr_b16 v[206:207], v94 offset:0x3200
	ds_read_b64_tr_b16 v[208:209], v94 offset:0x3a00
	s_waitcnt lgkmcnt(8)
	s_nop 0
	v_mfma_f32_32x32x16_bf16 v[48:63], v[64:67], v[82:85], v[48:63]
	v_mfma_f32_32x32x16_bf16 v[48:63], v[68:71], v[86:89], v[48:63]
	v_mfma_f32_32x32x16_bf16 v[48:63], v[72:75], v[90:93], v[48:63]
	v_mfma_f32_32x32x16_bf16 v[48:63], v[76:79], v[190:193], v[48:63]
	ds_read_b64_tr_b16 v[82:83], v94 offset:0x400
	ds_read_b64_tr_b16 v[84:85], v94 offset:0xc00
	ds_read_b64_tr_b16 v[86:87], v94 offset:0x1400
	ds_read_b64_tr_b16 v[88:89], v94 offset:0x1c00
	ds_read_b64_tr_b16 v[90:91], v94 offset:0x2400
	ds_read_b64_tr_b16 v[92:93], v94 offset:0x2c00
	ds_read_b64_tr_b16 v[190:191], v94 offset:0x3400
	ds_read_b64_tr_b16 v[192:193], v94 offset:0x3c00
	s_waitcnt lgkmcnt(8)
	v_mfma_f32_32x32x16_bf16 v[32:47], v[64:67], v[194:197], v[32:47]
	v_mfma_f32_32x32x16_bf16 v[32:47], v[68:71], v[198:201], v[32:47]
	v_mfma_f32_32x32x16_bf16 v[32:47], v[72:75], v[202:205], v[32:47]
	v_mfma_f32_32x32x16_bf16 v[32:47], v[76:79], v[206:209], v[32:47]
	ds_read_b64_tr_b16 v[194:195], v94 offset:0x600
	ds_read_b64_tr_b16 v[196:197], v94 offset:0xe00
	ds_read_b64_tr_b16 v[198:199], v94 offset:0x1600
	ds_read_b64_tr_b16 v[200:201], v94 offset:0x1e00
	ds_read_b64_tr_b16 v[202:203], v94 offset:0x2600
	ds_read_b64_tr_b16 v[204:205], v94 offset:0x2e00
	ds_read_b64_tr_b16 v[206:207], v94 offset:0x3600
	ds_read_b64_tr_b16 v[208:209], v94 offset:0x3e00
	s_waitcnt lgkmcnt(8)
	v_mfma_f32_32x32x16_bf16 v[16:31], v[64:67], v[82:85], v[16:31]
	v_mfma_f32_32x32x16_bf16 v[16:31], v[68:71], v[86:89], v[16:31]
	v_mfma_f32_32x32x16_bf16 v[16:31], v[72:75], v[90:93], v[16:31]
	v_mfma_f32_32x32x16_bf16 v[16:31], v[76:79], v[190:193], v[16:31]
	s_waitcnt lgkmcnt(0)
	s_and_b64 vcc, s[30:31], s[70:71]
	s_andn2_b64 vcc, exec, vcc
	s_cbranch_vccnz .Lattn_stage_skip
	s_mul_i32 s0, s87, 0x6400
	v_add_u32_e32 v214, s0, v173
	s_lshl_b32 s0, s77, 14
	s_add_i32 s0, s0, 0
	s_waitcnt vmcnt(2)
	ds_write_b128 v214, v[148:151] offset:49152
	s_waitcnt vmcnt(1)
	ds_write_b128 v214, v[156:159] offset:49280
	s_waitcnt vmcnt(0)
	ds_write_b128 v214, v[160:163] offset:49408
	v_add_u32_e32 v214, s0, v170
	ds_write_b128 v214, v[144:147]
	v_add_u32_e32 v214, s0, v171
	ds_write_b128 v214, v[152:155]
